# v50 with the tile-group census flag computed inside seam 2 (no load+wait at P1 start)
# speedup vs baseline: 1.0028x; 1.0028x over previous
.LBB0_161:
	v_cndmask_b32_e64 v0, 0, 1, s[46:47]
	v_cmp_ne_u32_e64 s[4:5], 1, v0
	s_and_b32 s8, s2, 63
	s_lshl_b32 s8, s8, 2
	s_add_i32 s8, s8, 15600
	v_mov_b32_e32 v0, s8
	global_load_dword v0, v0, s[52:53] sc1
	s_waitcnt vmcnt(0) lgkmcnt(0)
	s_barrier
	s_and_b32 s8, s90, 7
	s_lshl_b32 s8, s8, 2
	v_readfirstlane_b32 s9, v0
	s_lshr_b32 s9, s9, s8
	s_and_b32 s9, s9, 15
	s_cmp_eq_u32 s9, 4
	s_cselect_b32 s9, 1, 0
	v_writelane_b32 v242, s9, 13
	s_nop 1
	s_and_saveexec_b64 s[0:1], s[98:99]
	s_cbranch_execz .Lmy_s2_done
	v_readlane_b32 s8, v242, 13
	s_cmp_eq_u32 s8, 1
	s_cbranch_scc1 .Lmy_s2_uni
	buffer_wbl2 sc1
	s_waitcnt vmcnt(0)
